# FFN-out: accumulators start from 2*residual (residual tile read before the K loop, overlapping the pipeline fill), epilogue = 0.5*acc, pack, store, f32 sum of squares; no residual loads at the tile en
# baseline (speedup 1.0000x reference)
.LBB0_270:
	s_ashr_i32 s9, s8, 31
	s_lshl_b64 s[10:11], s[8:9], 21
	s_add_u32 s10, s33, s10
	s_addc_u32 s11, s96, s11
	s_and_b64 s[28:29], s[40:41], exec
	s_cselect_b32 s9, s11, s51
	s_cselect_b32 s27, s10, s50
	s_ashr_i32 s7, s6, 31
	s_lshl_b64 s[28:29], s[6:7], 21
	s_add_u32 s36, s52, s28
	s_addc_u32 s37, s53, s29
	s_and_b64 s[28:29], s[40:41], exec
	s_cselect_b32 s7, s37, s49
	s_cselect_b32 s28, s36, s48
	s_add_u32 s29, s48, 0x100
	s_addc_u32 s30, s49, 0
	s_add_u32 s82, s50, 0x100800
	s_addc_u32 s83, s51, 0
	s_mov_b32 s31, -2
	v_mbcnt_lo_u32_b32 v2, -1, 0
	v_mbcnt_hi_u32_b32 v2, -1, v2
	s_lshl_b32 s100, s25, 8
	s_or_b32 s100, s100, s59
	s_lshl_b32 s101, s26, 8
	s_add_i32 s101, s101, s58
	v_ashrrev_i32_e32 v3, 1, v2
	v_and_b32_e32 v3, -8, v3
	v_add_u32_e32 v4, s100, v3
	v_ashrrev_i32_e32 v5, 31, v4
	v_and_or_b32 v6, v2, 15, s101
	v_lshlrev_b64 v[8:9], 1, v[4:5]
	v_ashrrev_i32_e32 v7, 31, v6
	v_lshl_add_u64 v[10:11], s[42:43], 0, v[8:9]
	v_lshlrev_b64 v[12:13], 11, v[6:7]
	v_lshl_add_u64 v[10:11], v[10:11], 0, v[12:13]
	v_mov_b32_e32 v16, 0x8000
	v_mov_b32_e32 v17, 0
	global_load_dwordx4 v[190:193], v[10:11], off
	global_load_dwordx4 v[186:189], v[10:11], off offset:256
	v_lshl_add_u64 v[12:13], v[16:17], 0, v[10:11]
	global_load_dwordx4 v[182:185], v[12:13], off
	global_load_dwordx4 v[178:181], v[12:13], off offset:256
	v_lshl_add_u64 v[14:15], v[16:17], 1, v[10:11]
	global_load_dwordx4 v[174:177], v[14:15], off
	global_load_dwordx4 v[170:173], v[14:15], off offset:256
	v_lshl_add_u64 v[12:13], v[16:17], 0, v[14:15]
	global_load_dwordx4 v[166:169], v[12:13], off
	global_load_dwordx4 v[162:165], v[12:13], off offset:256
	v_lshl_add_u64 v[14:15], v[16:17], 3, v[10:11]
	global_load_dwordx4 v[158:161], v[14:15], off
	global_load_dwordx4 v[150:153], v[14:15], off offset:256
	v_lshl_add_u64 v[12:13], v[16:17], 0, v[14:15]
	global_load_dwordx4 v[142:145], v[12:13], off
	global_load_dwordx4 v[138:141], v[12:13], off offset:256
	v_lshl_add_u64 v[18:19], v[16:17], 1, v[14:15]
	global_load_dwordx4 v[126:129], v[18:19], off
	global_load_dwordx4 v[114:117], v[18:19], off offset:256
	v_lshl_add_u64 v[12:13], v[16:17], 0, v[18:19]
	global_load_dwordx4 v[106:109], v[12:13], off
	global_load_dwordx4 v[94:97], v[12:13], off offset:256
	s_waitcnt vmcnt(0)
	v_lshlrev_b32_e32 v6, 16, v94
	v_and_b32_e32 v7, 0xffff0000, v94
	v_pk_add_f32 v[6:7], v[6:7], v[6:7]
	v_lshlrev_b32_e32 v8, 16, v95
	v_and_b32_e32 v9, 0xffff0000, v95
	v_pk_add_f32 v[8:9], v[8:9], v[8:9]
	v_lshlrev_b32_e32 v2, 16, v96
	v_and_b32_e32 v3, 0xffff0000, v96
	v_pk_add_f32 v[2:3], v[2:3], v[2:3]
	v_lshlrev_b32_e32 v4, 16, v97
	v_and_b32_e32 v5, 0xffff0000, v97
	v_pk_add_f32 v[4:5], v[4:5], v[4:5]
	v_lshlrev_b32_e32 v14, 16, v106
	v_and_b32_e32 v15, 0xffff0000, v106
	v_pk_add_f32 v[14:15], v[14:15], v[14:15]
	v_lshlrev_b32_e32 v16, 16, v107
	v_and_b32_e32 v17, 0xffff0000, v107
	v_pk_add_f32 v[16:17], v[16:17], v[16:17]
	v_lshlrev_b32_e32 v10, 16, v108
	v_and_b32_e32 v11, 0xffff0000, v108
	v_pk_add_f32 v[10:11], v[10:11], v[10:11]
	v_lshlrev_b32_e32 v12, 16, v109
	v_and_b32_e32 v13, 0xffff0000, v109
	v_pk_add_f32 v[12:13], v[12:13], v[12:13]
	v_lshlrev_b32_e32 v22, 16, v114
	v_and_b32_e32 v23, 0xffff0000, v114
	v_pk_add_f32 v[22:23], v[22:23], v[22:23]
	v_lshlrev_b32_e32 v24, 16, v115
	v_and_b32_e32 v25, 0xffff0000, v115
	v_pk_add_f32 v[24:25], v[24:25], v[24:25]
	v_lshlrev_b32_e32 v18, 16, v116
	v_and_b32_e32 v19, 0xffff0000, v116
	v_pk_add_f32 v[18:19], v[18:19], v[18:19]
	v_lshlrev_b32_e32 v20, 16, v117
	v_and_b32_e32 v21, 0xffff0000, v117
	v_pk_add_f32 v[20:21], v[20:21], v[20:21]
	v_lshlrev_b32_e32 v30, 16, v126
	v_and_b32_e32 v31, 0xffff0000, v126
	v_pk_add_f32 v[30:31], v[30:31], v[30:31]
	v_lshlrev_b32_e32 v32, 16, v127
	v_and_b32_e32 v33, 0xffff0000, v127
	v_pk_add_f32 v[32:33], v[32:33], v[32:33]
	v_lshlrev_b32_e32 v26, 16, v128
	v_and_b32_e32 v27, 0xffff0000, v128
	v_pk_add_f32 v[26:27], v[26:27], v[26:27]
	v_lshlrev_b32_e32 v28, 16, v129
	v_and_b32_e32 v29, 0xffff0000, v129
	v_pk_add_f32 v[28:29], v[28:29], v[28:29]
	v_lshlrev_b32_e32 v38, 16, v138
	v_and_b32_e32 v39, 0xffff0000, v138
	v_pk_add_f32 v[38:39], v[38:39], v[38:39]
	v_lshlrev_b32_e32 v40, 16, v139
	v_and_b32_e32 v41, 0xffff0000, v139
	v_pk_add_f32 v[40:41], v[40:41], v[40:41]
	v_lshlrev_b32_e32 v34, 16, v140
	v_and_b32_e32 v35, 0xffff0000, v140
	v_pk_add_f32 v[34:35], v[34:35], v[34:35]
	v_lshlrev_b32_e32 v36, 16, v141
	v_and_b32_e32 v37, 0xffff0000, v141
	v_pk_add_f32 v[36:37], v[36:37], v[36:37]
	v_lshlrev_b32_e32 v46, 16, v142
	v_and_b32_e32 v47, 0xffff0000, v142
	v_pk_add_f32 v[46:47], v[46:47], v[46:47]
	v_lshlrev_b32_e32 v48, 16, v143
	v_and_b32_e32 v49, 0xffff0000, v143
	v_pk_add_f32 v[48:49], v[48:49], v[48:49]
	v_lshlrev_b32_e32 v42, 16, v144
	v_and_b32_e32 v43, 0xffff0000, v144
	v_pk_add_f32 v[42:43], v[42:43], v[42:43]
	v_lshlrev_b32_e32 v44, 16, v145
	v_and_b32_e32 v45, 0xffff0000, v145
	v_pk_add_f32 v[44:45], v[44:45], v[44:45]
	v_lshlrev_b32_e32 v54, 16, v150
	v_and_b32_e32 v55, 0xffff0000, v150
	v_pk_add_f32 v[54:55], v[54:55], v[54:55]
	v_lshlrev_b32_e32 v56, 16, v151
	v_and_b32_e32 v57, 0xffff0000, v151
	v_pk_add_f32 v[56:57], v[56:57], v[56:57]
	v_lshlrev_b32_e32 v50, 16, v152
	v_and_b32_e32 v51, 0xffff0000, v152
	v_pk_add_f32 v[50:51], v[50:51], v[50:51]
	v_lshlrev_b32_e32 v52, 16, v153
	v_and_b32_e32 v53, 0xffff0000, v153
	v_pk_add_f32 v[52:53], v[52:53], v[52:53]
	v_lshlrev_b32_e32 v62, 16, v158
	v_and_b32_e32 v63, 0xffff0000, v158
	v_pk_add_f32 v[62:63], v[62:63], v[62:63]
	v_lshlrev_b32_e32 v64, 16, v159
	v_and_b32_e32 v65, 0xffff0000, v159
	v_pk_add_f32 v[64:65], v[64:65], v[64:65]
	v_lshlrev_b32_e32 v58, 16, v160
	v_and_b32_e32 v59, 0xffff0000, v160
	v_pk_add_f32 v[58:59], v[58:59], v[58:59]
	v_lshlrev_b32_e32 v60, 16, v161
	v_and_b32_e32 v61, 0xffff0000, v161
	v_pk_add_f32 v[60:61], v[60:61], v[60:61]
	v_lshlrev_b32_e32 v70, 16, v162
	v_and_b32_e32 v71, 0xffff0000, v162
	v_pk_add_f32 v[70:71], v[70:71], v[70:71]
	v_lshlrev_b32_e32 v72, 16, v163
	v_and_b32_e32 v73, 0xffff0000, v163
	v_pk_add_f32 v[72:73], v[72:73], v[72:73]
	v_lshlrev_b32_e32 v66, 16, v164
	v_and_b32_e32 v67, 0xffff0000, v164
	v_pk_add_f32 v[66:67], v[66:67], v[66:67]
	v_lshlrev_b32_e32 v68, 16, v165
	v_and_b32_e32 v69, 0xffff0000, v165
	v_pk_add_f32 v[68:69], v[68:69], v[68:69]
	v_lshlrev_b32_e32 v78, 16, v166
	v_and_b32_e32 v79, 0xffff0000, v166
	v_pk_add_f32 v[78:79], v[78:79], v[78:79]
	v_lshlrev_b32_e32 v80, 16, v167
	v_and_b32_e32 v81, 0xffff0000, v167
	v_pk_add_f32 v[80:81], v[80:81], v[80:81]
	v_lshlrev_b32_e32 v74, 16, v168
	v_and_b32_e32 v75, 0xffff0000, v168
	v_pk_add_f32 v[74:75], v[74:75], v[74:75]
	v_lshlrev_b32_e32 v76, 16, v169
	v_and_b32_e32 v77, 0xffff0000, v169
	v_pk_add_f32 v[76:77], v[76:77], v[76:77]
	v_lshlrev_b32_e32 v86, 16, v170
	v_and_b32_e32 v87, 0xffff0000, v170
	v_pk_add_f32 v[86:87], v[86:87], v[86:87]
	v_lshlrev_b32_e32 v88, 16, v171
	v_and_b32_e32 v89, 0xffff0000, v171
	v_pk_add_f32 v[88:89], v[88:89], v[88:89]
	v_lshlrev_b32_e32 v82, 16, v172
	v_and_b32_e32 v83, 0xffff0000, v172
	v_pk_add_f32 v[82:83], v[82:83], v[82:83]
	v_lshlrev_b32_e32 v84, 16, v173
	v_and_b32_e32 v85, 0xffff0000, v173
	v_pk_add_f32 v[84:85], v[84:85], v[84:85]
	v_lshlrev_b32_e32 v98, 16, v174
	v_and_b32_e32 v99, 0xffff0000, v174
	v_pk_add_f32 v[98:99], v[98:99], v[98:99]
	v_lshlrev_b32_e32 v100, 16, v175
	v_and_b32_e32 v101, 0xffff0000, v175
	v_pk_add_f32 v[100:101], v[100:101], v[100:101]
	v_lshlrev_b32_e32 v90, 16, v176
	v_and_b32_e32 v91, 0xffff0000, v176
	v_pk_add_f32 v[90:91], v[90:91], v[90:91]
	v_lshlrev_b32_e32 v92, 16, v177
	v_and_b32_e32 v93, 0xffff0000, v177
	v_pk_add_f32 v[92:93], v[92:93], v[92:93]
	v_lshlrev_b32_e32 v110, 16, v178
	v_and_b32_e32 v111, 0xffff0000, v178
	v_pk_add_f32 v[110:111], v[110:111], v[110:111]
	v_lshlrev_b32_e32 v112, 16, v179
	v_and_b32_e32 v113, 0xffff0000, v179
	v_pk_add_f32 v[112:113], v[112:113], v[112:113]
	v_lshlrev_b32_e32 v102, 16, v180
	v_and_b32_e32 v103, 0xffff0000, v180
	v_pk_add_f32 v[102:103], v[102:103], v[102:103]
	v_lshlrev_b32_e32 v104, 16, v181
	v_and_b32_e32 v105, 0xffff0000, v181
	v_pk_add_f32 v[104:105], v[104:105], v[104:105]
	v_lshlrev_b32_e32 v122, 16, v182
	v_and_b32_e32 v123, 0xffff0000, v182
	v_pk_add_f32 v[122:123], v[122:123], v[122:123]
	v_lshlrev_b32_e32 v124, 16, v183
	v_and_b32_e32 v125, 0xffff0000, v183
	v_pk_add_f32 v[124:125], v[124:125], v[124:125]
	v_lshlrev_b32_e32 v118, 16, v184
	v_and_b32_e32 v119, 0xffff0000, v184
	v_pk_add_f32 v[118:119], v[118:119], v[118:119]
	v_lshlrev_b32_e32 v120, 16, v185
	v_and_b32_e32 v121, 0xffff0000, v185
	v_pk_add_f32 v[120:121], v[120:121], v[120:121]
	v_lshlrev_b32_e32 v134, 16, v186
	v_and_b32_e32 v135, 0xffff0000, v186
	v_pk_add_f32 v[134:135], v[134:135], v[134:135]
	v_lshlrev_b32_e32 v136, 16, v187
	v_and_b32_e32 v137, 0xffff0000, v187
	v_pk_add_f32 v[136:137], v[136:137], v[136:137]
	v_lshlrev_b32_e32 v130, 16, v188
	v_and_b32_e32 v131, 0xffff0000, v188
	v_pk_add_f32 v[130:131], v[130:131], v[130:131]
	v_lshlrev_b32_e32 v132, 16, v189
	v_and_b32_e32 v133, 0xffff0000, v189
	v_pk_add_f32 v[132:133], v[132:133], v[132:133]
	v_lshlrev_b32_e32 v154, 16, v190
	v_and_b32_e32 v155, 0xffff0000, v190
	v_pk_add_f32 v[154:155], v[154:155], v[154:155]
	v_lshlrev_b32_e32 v156, 16, v191
	v_and_b32_e32 v157, 0xffff0000, v191
	v_pk_add_f32 v[156:157], v[156:157], v[156:157]
	v_lshlrev_b32_e32 v146, 16, v192
	v_and_b32_e32 v147, 0xffff0000, v192
	v_pk_add_f32 v[146:147], v[146:147], v[146:147]
	v_lshlrev_b32_e32 v148, 16, v193
	v_and_b32_e32 v149, 0xffff0000, v193
	v_pk_add_f32 v[148:149], v[148:149], v[148:149]

.LBB0_274:
	v_mbcnt_lo_u32_b32 v94, -1, 0
	v_mbcnt_hi_u32_b32 v94, -1, v94
	s_lshl_b32 s9, s25, 8
	v_ashrrev_i32_e32 v95, 1, v94
	s_lshl_b32 s7, s26, 8
	s_or_b32 s9, s9, s59
	v_and_b32_e32 v95, -8, v95
	s_add_i32 s7, s7, s58
	v_add_u32_e32 v204, s9, v95
	v_ashrrev_i32_e32 v205, 31, v204
	v_and_or_b32 v234, v94, 15, s7
	v_lshlrev_b64 v[236:237], 1, v[204:205]
	v_ashrrev_i32_e32 v235, 31, v234
	v_cmp_gt_u32_e32 vcc, 16, v94
	v_lshlrev_b64 v[238:239], 11, v[234:235]
	v_or_b32_e32 v230, 16, v234
	v_ashrrev_i32_e32 v231, 31, v230
	v_or_b32_e32 v210, 32, v234
	v_lshlrev_b64 v[232:233], 11, v[230:231]
	v_ashrrev_i32_e32 v211, 31, v210
	v_or_b32_e32 v226, 48, v234
	v_lshlrev_b64 v[212:213], 11, v[210:211]
	v_ashrrev_i32_e32 v227, 31, v226
	v_add_u32_e32 v222, 0x80, v234
	v_lshlrev_b64 v[228:229], 11, v[226:227]
	v_ashrrev_i32_e32 v223, 31, v222
	v_add_u32_e32 v218, 0x90, v234
	v_lshlrev_b64 v[224:225], 11, v[222:223]
	v_ashrrev_i32_e32 v219, 31, v218
	v_add_u32_e32 v214, 0xa0, v234
	v_add_u32_e32 v206, 0xb0, v234
	v_lshlrev_b64 v[220:221], 11, v[218:219]
	v_ashrrev_i32_e32 v215, 31, v214
	v_ashrrev_i32_e32 v207, 31, v206
	v_lshlrev_b64 v[216:217], 11, v[214:215]
	v_lshlrev_b64 v[208:209], 11, v[206:207]
	s_lshl_b32 s82, s25, 2
	s_ashr_i32 s83, s82, 31
	s_mov_b32 s31, 0xf800000
	s_lshl_b32 s76, s55, 2
	v_pk_mul_f32 v[154:155], v[154:155], 0.5 op_sel_hi:[1,0]
	v_pk_mul_f32 v[156:157], v[156:157], 0.5 op_sel_hi:[1,0]
	v_pk_mul_f32 v[146:147], v[146:147], 0.5 op_sel_hi:[1,0]
	v_pk_mul_f32 v[148:149], v[148:149], 0.5 op_sel_hi:[1,0]
	v_cvt_pk_bf16_f32 v190, v154, v155
	v_pk_mul_f32 v[246:247], v[154:155], v[154:155]
	v_cvt_pk_bf16_f32 v191, v156, v157
	v_pk_fma_f32 v[246:247], v[156:157], v[156:157], v[246:247]
	v_cvt_pk_bf16_f32 v192, v146, v147
	v_pk_fma_f32 v[246:247], v[146:147], v[146:147], v[246:247]
	v_cvt_pk_bf16_f32 v193, v148, v149
	v_pk_fma_f32 v[246:247], v[148:149], v[148:149], v[246:247]
	v_lshl_add_u64 v[244:245], s[88:89], 0, v[238:239]
	v_lshl_add_u64 v[244:245], v[244:245], 0, v[236:237]
	global_store_dwordx4 v[244:245], v[190:193], off
	v_pk_mul_f32 v[134:135], v[134:135], 0.5 op_sel_hi:[1,0]
	v_pk_mul_f32 v[136:137], v[136:137], 0.5 op_sel_hi:[1,0]
	v_pk_mul_f32 v[130:131], v[130:131], 0.5 op_sel_hi:[1,0]
	v_pk_mul_f32 v[132:133], v[132:133], 0.5 op_sel_hi:[1,0]
	v_cvt_pk_bf16_f32 v186, v134, v135
	v_pk_fma_f32 v[246:247], v[134:135], v[134:135], v[246:247]
	v_cvt_pk_bf16_f32 v187, v136, v137
	v_pk_fma_f32 v[246:247], v[136:137], v[136:137], v[246:247]
	v_cvt_pk_bf16_f32 v188, v130, v131
	v_pk_fma_f32 v[246:247], v[130:131], v[130:131], v[246:247]
	v_cvt_pk_bf16_f32 v189, v132, v133
	v_pk_fma_f32 v[246:247], v[132:133], v[132:133], v[246:247]
	global_store_dwordx4 v[244:245], v[186:189], off offset:256
	v_add_f32_e32 v246, v246, v247
	v_mov_b32_e32 v146, v246
	v_lshlrev_b64 v[156:157], 6, v[234:235]
	v_lshl_add_u64 v[156:157], s[38:39], 0, v[156:157]
	v_permlane16_swap_b32_e32 v146, v246
	v_add_f32_e32 v246, v146, v246
	v_mov_b32_e32 v146, v246
	v_lshl_add_u64 v[156:157], s[82:83], 2, v[156:157]
	v_lshl_add_u64 v[156:157], v[156:157], 0, s[76:77]
	v_permlane32_swap_b32_e32 v146, v246
	v_add_f32_e32 v246, v146, v246
	s_and_saveexec_b64 s[48:49], vcc
	global_store_dword v[156:157], v246, off
	s_or_b64 exec, exec, s[48:49]
	v_pk_mul_f32 v[122:123], v[122:123], 0.5 op_sel_hi:[1,0]
	v_pk_mul_f32 v[124:125], v[124:125], 0.5 op_sel_hi:[1,0]
	v_pk_mul_f32 v[118:119], v[118:119], 0.5 op_sel_hi:[1,0]
	v_pk_mul_f32 v[120:121], v[120:121], 0.5 op_sel_hi:[1,0]
	v_cvt_pk_bf16_f32 v182, v122, v123
	v_pk_mul_f32 v[246:247], v[122:123], v[122:123]
	v_cvt_pk_bf16_f32 v183, v124, v125
	v_pk_fma_f32 v[246:247], v[124:125], v[124:125], v[246:247]
	v_cvt_pk_bf16_f32 v184, v118, v119
	v_pk_fma_f32 v[246:247], v[118:119], v[118:119], v[246:247]
	v_cvt_pk_bf16_f32 v185, v120, v121
	v_pk_fma_f32 v[246:247], v[120:121], v[120:121], v[246:247]
	v_lshl_add_u64 v[244:245], s[88:89], 0, v[232:233]
	v_lshl_add_u64 v[244:245], v[244:245], 0, v[236:237]
	global_store_dwordx4 v[244:245], v[182:185], off
	v_pk_mul_f32 v[110:111], v[110:111], 0.5 op_sel_hi:[1,0]
	v_pk_mul_f32 v[112:113], v[112:113], 0.5 op_sel_hi:[1,0]
	v_pk_mul_f32 v[102:103], v[102:103], 0.5 op_sel_hi:[1,0]
	v_pk_mul_f32 v[104:105], v[104:105], 0.5 op_sel_hi:[1,0]
	v_cvt_pk_bf16_f32 v178, v110, v111
	v_pk_fma_f32 v[246:247], v[110:111], v[110:111], v[246:247]
	v_cvt_pk_bf16_f32 v179, v112, v113
	v_pk_fma_f32 v[246:247], v[112:113], v[112:113], v[246:247]
	v_cvt_pk_bf16_f32 v180, v102, v103
	v_pk_fma_f32 v[246:247], v[102:103], v[102:103], v[246:247]
	v_cvt_pk_bf16_f32 v181, v104, v105
	v_pk_fma_f32 v[246:247], v[104:105], v[104:105], v[246:247]
	global_store_dwordx4 v[244:245], v[178:181], off offset:256
	v_add_f32_e32 v246, v246, v247
	v_mov_b32_e32 v118, v246
	v_lshlrev_b64 v[124:125], 6, v[230:231]
	v_lshl_add_u64 v[124:125], s[38:39], 0, v[124:125]
	v_permlane16_swap_b32_e32 v118, v246
	v_add_f32_e32 v246, v118, v246
	v_mov_b32_e32 v118, v246
	v_lshl_add_u64 v[124:125], s[82:83], 2, v[124:125]
	v_lshl_add_u64 v[124:125], v[124:125], 0, s[76:77]
	v_permlane32_swap_b32_e32 v118, v246
	v_add_f32_e32 v246, v118, v246
	s_and_saveexec_b64 s[48:49], vcc
	global_store_dword v[124:125], v246, off
	s_or_b64 exec, exec, s[48:49]
	v_pk_mul_f32 v[98:99], v[98:99], 0.5 op_sel_hi:[1,0]
	v_pk_mul_f32 v[100:101], v[100:101], 0.5 op_sel_hi:[1,0]
	v_pk_mul_f32 v[90:91], v[90:91], 0.5 op_sel_hi:[1,0]
	v_pk_mul_f32 v[92:93], v[92:93], 0.5 op_sel_hi:[1,0]
	v_cvt_pk_bf16_f32 v174, v98, v99
	v_pk_mul_f32 v[246:247], v[98:99], v[98:99]
	v_cvt_pk_bf16_f32 v175, v100, v101
	v_pk_fma_f32 v[246:247], v[100:101], v[100:101], v[246:247]
	v_cvt_pk_bf16_f32 v176, v90, v91
	v_pk_fma_f32 v[246:247], v[90:91], v[90:91], v[246:247]
	v_cvt_pk_bf16_f32 v177, v92, v93
	v_pk_fma_f32 v[246:247], v[92:93], v[92:93], v[246:247]
	v_lshl_add_u64 v[244:245], s[88:89], 0, v[212:213]
	v_lshl_add_u64 v[244:245], v[244:245], 0, v[236:237]
	global_store_dwordx4 v[244:245], v[174:177], off
	v_pk_mul_f32 v[86:87], v[86:87], 0.5 op_sel_hi:[1,0]
	v_pk_mul_f32 v[88:89], v[88:89], 0.5 op_sel_hi:[1,0]
	v_pk_mul_f32 v[82:83], v[82:83], 0.5 op_sel_hi:[1,0]
	v_pk_mul_f32 v[84:85], v[84:85], 0.5 op_sel_hi:[1,0]
	v_cvt_pk_bf16_f32 v170, v86, v87
	v_pk_fma_f32 v[246:247], v[86:87], v[86:87], v[246:247]
	v_cvt_pk_bf16_f32 v171, v88, v89
	v_pk_fma_f32 v[246:247], v[88:89], v[88:89], v[246:247]
	v_cvt_pk_bf16_f32 v172, v82, v83
	v_pk_fma_f32 v[246:247], v[82:83], v[82:83], v[246:247]
	v_cvt_pk_bf16_f32 v173, v84, v85
	v_pk_fma_f32 v[246:247], v[84:85], v[84:85], v[246:247]
	global_store_dwordx4 v[244:245], v[170:173], off offset:256
	v_add_f32_e32 v246, v246, v247
	v_mov_b32_e32 v90, v246
	v_lshlrev_b64 v[100:101], 6, v[210:211]
	v_lshl_add_u64 v[100:101], s[38:39], 0, v[100:101]
	v_permlane16_swap_b32_e32 v90, v246
	v_add_f32_e32 v246, v90, v246
	v_mov_b32_e32 v90, v246
	v_lshl_add_u64 v[100:101], s[82:83], 2, v[100:101]
	v_lshl_add_u64 v[100:101], v[100:101], 0, s[76:77]
	v_permlane32_swap_b32_e32 v90, v246
	v_add_f32_e32 v246, v90, v246
	s_and_saveexec_b64 s[48:49], vcc
	global_store_dword v[100:101], v246, off
	s_or_b64 exec, exec, s[48:49]
	v_pk_mul_f32 v[78:79], v[78:79], 0.5 op_sel_hi:[1,0]
	v_pk_mul_f32 v[80:81], v[80:81], 0.5 op_sel_hi:[1,0]
	v_pk_mul_f32 v[74:75], v[74:75], 0.5 op_sel_hi:[1,0]
	v_pk_mul_f32 v[76:77], v[76:77], 0.5 op_sel_hi:[1,0]
	v_cvt_pk_bf16_f32 v166, v78, v79
	v_pk_mul_f32 v[246:247], v[78:79], v[78:79]
	v_cvt_pk_bf16_f32 v167, v80, v81
	v_pk_fma_f32 v[246:247], v[80:81], v[80:81], v[246:247]
	v_cvt_pk_bf16_f32 v168, v74, v75
	v_pk_fma_f32 v[246:247], v[74:75], v[74:75], v[246:247]
	v_cvt_pk_bf16_f32 v169, v76, v77
	v_pk_fma_f32 v[246:247], v[76:77], v[76:77], v[246:247]
	v_lshl_add_u64 v[244:245], s[88:89], 0, v[228:229]
	v_lshl_add_u64 v[244:245], v[244:245], 0, v[236:237]
	global_store_dwordx4 v[244:245], v[166:169], off
	v_pk_mul_f32 v[70:71], v[70:71], 0.5 op_sel_hi:[1,0]
	v_pk_mul_f32 v[72:73], v[72:73], 0.5 op_sel_hi:[1,0]
	v_pk_mul_f32 v[66:67], v[66:67], 0.5 op_sel_hi:[1,0]
	v_pk_mul_f32 v[68:69], v[68:69], 0.5 op_sel_hi:[1,0]
	v_cvt_pk_bf16_f32 v162, v70, v71
	v_pk_fma_f32 v[246:247], v[70:71], v[70:71], v[246:247]
	v_cvt_pk_bf16_f32 v163, v72, v73
	v_pk_fma_f32 v[246:247], v[72:73], v[72:73], v[246:247]
	v_cvt_pk_bf16_f32 v164, v66, v67
	v_pk_fma_f32 v[246:247], v[66:67], v[66:67], v[246:247]
	v_cvt_pk_bf16_f32 v165, v68, v69
	v_pk_fma_f32 v[246:247], v[68:69], v[68:69], v[246:247]
	global_store_dwordx4 v[244:245], v[162:165], off offset:256
	v_add_f32_e32 v246, v246, v247
	v_mov_b32_e32 v74, v246
	v_lshlrev_b64 v[80:81], 6, v[226:227]
	v_lshl_add_u64 v[80:81], s[38:39], 0, v[80:81]
	v_permlane16_swap_b32_e32 v74, v246
	v_add_f32_e32 v246, v74, v246
	v_mov_b32_e32 v74, v246
	v_lshl_add_u64 v[80:81], s[82:83], 2, v[80:81]
	v_lshl_add_u64 v[80:81], v[80:81], 0, s[76:77]
	v_permlane32_swap_b32_e32 v74, v246
	v_add_f32_e32 v246, v74, v246
	s_and_saveexec_b64 s[48:49], vcc
	global_store_dword v[80:81], v246, off
	s_or_b64 exec, exec, s[48:49]
	v_pk_mul_f32 v[62:63], v[62:63], 0.5 op_sel_hi:[1,0]
	v_pk_mul_f32 v[64:65], v[64:65], 0.5 op_sel_hi:[1,0]
	v_pk_mul_f32 v[58:59], v[58:59], 0.5 op_sel_hi:[1,0]
	v_pk_mul_f32 v[60:61], v[60:61], 0.5 op_sel_hi:[1,0]
	v_cvt_pk_bf16_f32 v158, v62, v63
	v_pk_mul_f32 v[246:247], v[62:63], v[62:63]
	v_cvt_pk_bf16_f32 v159, v64, v65
	v_pk_fma_f32 v[246:247], v[64:65], v[64:65], v[246:247]
	v_cvt_pk_bf16_f32 v160, v58, v59
	v_pk_fma_f32 v[246:247], v[58:59], v[58:59], v[246:247]
	v_cvt_pk_bf16_f32 v161, v60, v61
	v_pk_fma_f32 v[246:247], v[60:61], v[60:61], v[246:247]
	v_lshl_add_u64 v[244:245], s[88:89], 0, v[224:225]
	v_lshl_add_u64 v[244:245], v[244:245], 0, v[236:237]
	global_store_dwordx4 v[244:245], v[158:161], off
	v_pk_mul_f32 v[54:55], v[54:55], 0.5 op_sel_hi:[1,0]
	v_pk_mul_f32 v[56:57], v[56:57], 0.5 op_sel_hi:[1,0]
	v_pk_mul_f32 v[50:51], v[50:51], 0.5 op_sel_hi:[1,0]
	v_pk_mul_f32 v[52:53], v[52:53], 0.5 op_sel_hi:[1,0]
	v_cvt_pk_bf16_f32 v150, v54, v55
	v_pk_fma_f32 v[246:247], v[54:55], v[54:55], v[246:247]
	v_cvt_pk_bf16_f32 v151, v56, v57
	v_pk_fma_f32 v[246:247], v[56:57], v[56:57], v[246:247]
	v_cvt_pk_bf16_f32 v152, v50, v51
	v_pk_fma_f32 v[246:247], v[50:51], v[50:51], v[246:247]
	v_cvt_pk_bf16_f32 v153, v52, v53
	v_pk_fma_f32 v[246:247], v[52:53], v[52:53], v[246:247]
	global_store_dwordx4 v[244:245], v[150:153], off offset:256
	v_add_f32_e32 v246, v246, v247
	v_mov_b32_e32 v58, v246
	v_lshlrev_b64 v[64:65], 6, v[222:223]
	v_lshl_add_u64 v[64:65], s[38:39], 0, v[64:65]
	v_permlane16_swap_b32_e32 v58, v246
	v_add_f32_e32 v246, v58, v246
	v_mov_b32_e32 v58, v246
	v_lshl_add_u64 v[64:65], s[82:83], 2, v[64:65]
	v_lshl_add_u64 v[64:65], v[64:65], 0, s[76:77]
	v_permlane32_swap_b32_e32 v58, v246
	v_add_f32_e32 v246, v58, v246
	s_and_saveexec_b64 s[48:49], vcc
	global_store_dword v[64:65], v246, off
	s_or_b64 exec, exec, s[48:49]
	v_pk_mul_f32 v[46:47], v[46:47], 0.5 op_sel_hi:[1,0]
	v_pk_mul_f32 v[48:49], v[48:49], 0.5 op_sel_hi:[1,0]
	v_pk_mul_f32 v[42:43], v[42:43], 0.5 op_sel_hi:[1,0]
	v_pk_mul_f32 v[44:45], v[44:45], 0.5 op_sel_hi:[1,0]
	v_cvt_pk_bf16_f32 v142, v46, v47
	v_pk_mul_f32 v[246:247], v[46:47], v[46:47]
	v_cvt_pk_bf16_f32 v143, v48, v49
	v_pk_fma_f32 v[246:247], v[48:49], v[48:49], v[246:247]
	v_cvt_pk_bf16_f32 v144, v42, v43
	v_pk_fma_f32 v[246:247], v[42:43], v[42:43], v[246:247]
	v_cvt_pk_bf16_f32 v145, v44, v45
	v_pk_fma_f32 v[246:247], v[44:45], v[44:45], v[246:247]
	v_lshl_add_u64 v[244:245], s[88:89], 0, v[220:221]
	v_lshl_add_u64 v[244:245], v[244:245], 0, v[236:237]
	global_store_dwordx4 v[244:245], v[142:145], off
	v_pk_mul_f32 v[38:39], v[38:39], 0.5 op_sel_hi:[1,0]
	v_pk_mul_f32 v[40:41], v[40:41], 0.5 op_sel_hi:[1,0]
	v_pk_mul_f32 v[34:35], v[34:35], 0.5 op_sel_hi:[1,0]
	v_pk_mul_f32 v[36:37], v[36:37], 0.5 op_sel_hi:[1,0]
	v_cvt_pk_bf16_f32 v138, v38, v39
	v_pk_fma_f32 v[246:247], v[38:39], v[38:39], v[246:247]
	v_cvt_pk_bf16_f32 v139, v40, v41
	v_pk_fma_f32 v[246:247], v[40:41], v[40:41], v[246:247]
	v_cvt_pk_bf16_f32 v140, v34, v35
	v_pk_fma_f32 v[246:247], v[34:35], v[34:35], v[246:247]
	v_cvt_pk_bf16_f32 v141, v36, v37
	v_pk_fma_f32 v[246:247], v[36:37], v[36:37], v[246:247]
	global_store_dwordx4 v[244:245], v[138:141], off offset:256
	v_add_f32_e32 v246, v246, v247
	v_mov_b32_e32 v42, v246
	v_lshlrev_b64 v[48:49], 6, v[218:219]
	v_lshl_add_u64 v[48:49], s[38:39], 0, v[48:49]
	v_permlane16_swap_b32_e32 v42, v246
	v_add_f32_e32 v246, v42, v246
	v_mov_b32_e32 v42, v246
	v_lshl_add_u64 v[48:49], s[82:83], 2, v[48:49]
	v_lshl_add_u64 v[48:49], v[48:49], 0, s[76:77]
	v_permlane32_swap_b32_e32 v42, v246
	v_add_f32_e32 v246, v42, v246
	s_and_saveexec_b64 s[48:49], vcc
	global_store_dword v[48:49], v246, off
	s_or_b64 exec, exec, s[48:49]
	v_pk_mul_f32 v[30:31], v[30:31], 0.5 op_sel_hi:[1,0]
	v_pk_mul_f32 v[32:33], v[32:33], 0.5 op_sel_hi:[1,0]
	v_pk_mul_f32 v[26:27], v[26:27], 0.5 op_sel_hi:[1,0]
	v_pk_mul_f32 v[28:29], v[28:29], 0.5 op_sel_hi:[1,0]
	v_cvt_pk_bf16_f32 v126, v30, v31
	v_pk_mul_f32 v[246:247], v[30:31], v[30:31]
	v_cvt_pk_bf16_f32 v127, v32, v33
	v_pk_fma_f32 v[246:247], v[32:33], v[32:33], v[246:247]
	v_cvt_pk_bf16_f32 v128, v26, v27
	v_pk_fma_f32 v[246:247], v[26:27], v[26:27], v[246:247]
	v_cvt_pk_bf16_f32 v129, v28, v29
	v_pk_fma_f32 v[246:247], v[28:29], v[28:29], v[246:247]
	v_lshl_add_u64 v[244:245], s[88:89], 0, v[216:217]
	v_lshl_add_u64 v[244:245], v[244:245], 0, v[236:237]
	global_store_dwordx4 v[244:245], v[126:129], off
	v_pk_mul_f32 v[22:23], v[22:23], 0.5 op_sel_hi:[1,0]
	v_pk_mul_f32 v[24:25], v[24:25], 0.5 op_sel_hi:[1,0]
	v_pk_mul_f32 v[18:19], v[18:19], 0.5 op_sel_hi:[1,0]
	v_pk_mul_f32 v[20:21], v[20:21], 0.5 op_sel_hi:[1,0]
	v_cvt_pk_bf16_f32 v114, v22, v23
	v_pk_fma_f32 v[246:247], v[22:23], v[22:23], v[246:247]
	v_cvt_pk_bf16_f32 v115, v24, v25
	v_pk_fma_f32 v[246:247], v[24:25], v[24:25], v[246:247]
	v_cvt_pk_bf16_f32 v116, v18, v19
	v_pk_fma_f32 v[246:247], v[18:19], v[18:19], v[246:247]
	v_cvt_pk_bf16_f32 v117, v20, v21
	v_pk_fma_f32 v[246:247], v[20:21], v[20:21], v[246:247]
	global_store_dwordx4 v[244:245], v[114:117], off offset:256
	v_add_f32_e32 v246, v246, v247
	v_mov_b32_e32 v26, v246
	v_lshlrev_b64 v[32:33], 6, v[214:215]
	v_lshl_add_u64 v[32:33], s[38:39], 0, v[32:33]
	v_permlane16_swap_b32_e32 v26, v246
	v_add_f32_e32 v246, v26, v246
	v_mov_b32_e32 v26, v246
	v_lshl_add_u64 v[32:33], s[82:83], 2, v[32:33]
	v_lshl_add_u64 v[32:33], v[32:33], 0, s[76:77]
	v_permlane32_swap_b32_e32 v26, v246
	v_add_f32_e32 v246, v26, v246
	s_and_saveexec_b64 s[48:49], vcc
	global_store_dword v[32:33], v246, off
	s_or_b64 exec, exec, s[48:49]
	v_pk_mul_f32 v[14:15], v[14:15], 0.5 op_sel_hi:[1,0]
	v_pk_mul_f32 v[16:17], v[16:17], 0.5 op_sel_hi:[1,0]
	v_pk_mul_f32 v[10:11], v[10:11], 0.5 op_sel_hi:[1,0]
	v_pk_mul_f32 v[12:13], v[12:13], 0.5 op_sel_hi:[1,0]
	v_cvt_pk_bf16_f32 v106, v14, v15
	v_pk_mul_f32 v[246:247], v[14:15], v[14:15]
	v_cvt_pk_bf16_f32 v107, v16, v17
	v_pk_fma_f32 v[246:247], v[16:17], v[16:17], v[246:247]
	v_cvt_pk_bf16_f32 v108, v10, v11
	v_pk_fma_f32 v[246:247], v[10:11], v[10:11], v[246:247]
	v_cvt_pk_bf16_f32 v109, v12, v13
	v_pk_fma_f32 v[246:247], v[12:13], v[12:13], v[246:247]
	v_lshl_add_u64 v[244:245], s[88:89], 0, v[208:209]
	v_lshl_add_u64 v[244:245], v[244:245], 0, v[236:237]
	global_store_dwordx4 v[244:245], v[106:109], off
	v_pk_mul_f32 v[6:7], v[6:7], 0.5 op_sel_hi:[1,0]
	v_pk_mul_f32 v[8:9], v[8:9], 0.5 op_sel_hi:[1,0]
	v_pk_mul_f32 v[2:3], v[2:3], 0.5 op_sel_hi:[1,0]
	v_pk_mul_f32 v[4:5], v[4:5], 0.5 op_sel_hi:[1,0]
	v_cvt_pk_bf16_f32 v94, v6, v7
	v_pk_fma_f32 v[246:247], v[6:7], v[6:7], v[246:247]
	v_cvt_pk_bf16_f32 v95, v8, v9
	v_pk_fma_f32 v[246:247], v[8:9], v[8:9], v[246:247]
	v_cvt_pk_bf16_f32 v96, v2, v3
	v_pk_fma_f32 v[246:247], v[2:3], v[2:3], v[246:247]
	v_cvt_pk_bf16_f32 v97, v4, v5
	v_pk_fma_f32 v[246:247], v[4:5], v[4:5], v[246:247]
	global_store_dwordx4 v[244:245], v[94:97], off offset:256
	v_add_f32_e32 v246, v246, v247
	v_mov_b32_e32 v10, v246
	v_lshlrev_b64 v[16:17], 6, v[206:207]
	v_lshl_add_u64 v[16:17], s[38:39], 0, v[16:17]
	v_permlane16_swap_b32_e32 v10, v246
	v_add_f32_e32 v246, v10, v246
	v_mov_b32_e32 v10, v246
	v_lshl_add_u64 v[16:17], s[82:83], 2, v[16:17]
	v_lshl_add_u64 v[16:17], v[16:17], 0, s[76:77]
	v_permlane32_swap_b32_e32 v10, v246
	v_add_f32_e32 v246, v10, v246
	s_and_saveexec_b64 s[48:49], vcc
	global_store_dword v[16:17], v246, off
	s_or_b64 exec, exec, s[48:49]
	s_andn2_b64 vcc, exec, s[40:41]
	s_mov_b64 s[40:41], -1
	s_cbranch_vccnz .LBB0_263
	s_andn2_b64 vcc, exec, s[0:1]
	s_cbranch_vccnz .LBB0_262
	s_barrier
	s_branch .LBB0_262
